# forget-logit job epilogue: four head biases loaded together instead of one reload per head behind vmcnt(0)
# baseline (speedup 1.0000x reference)
.LBB0_485:
	v_mov_b32_e32 v2, 0
	v_mov_b32_e32 v3, 0
	v_mov_b32_e32 v4, 0
	v_mov_b32_e32 v5, 0
	v_readfirstlane_b32 s6, v25
	s_mov_b32 s13, m0
	v_and_b32_e32 v29, 63, v182
	v_lshrrev_b32_e32 v30, 4, v29
	v_and_b32_e32 v31, 15, v29
	v_xor_b32_e32 v32, v31, v30
	v_lshlrev_b32_e32 v33, 11, v30
	v_xor_b32_e32 v0, 0, v32
	v_lshl_add_u32 v90, v0, 4, v33
	v_xor_b32_e32 v0, 4, v32
	v_lshl_add_u32 v91, v0, 4, v33
	v_xor_b32_e32 v0, 8, v32
	v_lshl_add_u32 v92, v0, 4, v33
	v_xor_b32_e32 v0, 12, v32
	v_lshl_add_u32 v93, v0, 4, v33
	s_lshr_b32 s7, s6, 4
	s_lshl_b32 s8, s4, 7
	s_add_i32 s8, s8, s6
	s_lshl_b32 s8, s8, 11
	s_add_u32 s10, s70, 0x2448000
	s_addc_u32 s11, s71, 0
	s_add_u32 s10, s10, s8
	s_addc_u32 s11, s11, 0
	s_lshl_b32 s12, s7, 13
	v_lshlrev_b32_e32 v33, 8, v31
	v_add_u32_e32 v33, s12, v33
	v_or_b32_e32 v0, 0, v30
	v_xor_b32_e32 v0, v0, v31
	v_lshl_add_u32 v34, v0, 4, v33
	v_or_b32_e32 v0, 4, v30
	v_xor_b32_e32 v0, v0, v31
	v_lshl_add_u32 v35, v0, 4, v33
	v_or_b32_e32 v0, 8, v30
	v_xor_b32_e32 v0, v0, v31
	v_lshl_add_u32 v36, v0, 4, v33
	v_or_b32_e32 v0, 12, v30
	v_xor_b32_e32 v0, v0, v31
	v_lshl_add_u32 v37, v0, 4, v33
	v_lshlrev_b32_e32 v33, 11, v31
	v_add_u32_e32 v33, 0x10000, v33
	v_or_b32_e32 v0, 0, v30
	v_xor_b32_e32 v0, v0, v31
	v_lshl_add_u32 v38, v0, 4, v33
	v_or_b32_e32 v0, 4, v30
	v_xor_b32_e32 v0, v0, v31
	v_lshl_add_u32 v39, v0, 4, v33
	v_or_b32_e32 v0, 8, v30
	v_xor_b32_e32 v0, v0, v31
	v_lshl_add_u32 v40, v0, 4, v33
	v_or_b32_e32 v0, 12, v30
	v_xor_b32_e32 v0, v0, v31
	v_lshl_add_u32 v41, v0, 4, v33
	v_readlane_b32 s0, v251, 49
	v_readlane_b32 s1, v251, 50
	s_lshl_b32 s8, s16, 15
	s_sub_u32 s0, s0, 0x200
	s_subb_u32 s1, s1, 0
	s_add_u32 s0, s0, s8
	s_addc_u32 s1, s1, 0
	s_lshl_b32 s8, s7, 1
	v_xor_b32_e32 v0, s8, v29
	v_lshlrev_b32_e32 v0, 4, v0
	s_lshl_b32 s9, s8, 11
	s_add_i32 s9, s9, 0x0
	v_add_u32_e32 v0, s9, v0
	v_lshl_add_u64 v[94:95], s[0:1], 0, v[0:1]
	s_add_i32 s9, s9, 0x10000
	s_mov_b32 m0, s9
	s_nop 0
	global_load_lds_dwordx4 v[94:95], off
	s_lshl_b32 s8, s7, 1
	v_xor_b32_e32 v0, s8, v29
	v_lshlrev_b32_e32 v0, 4, v0
	s_lshl_b32 s9, s8, 11
	s_add_i32 s9, s9, 0x400
	v_add_u32_e32 v0, s9, v0
	v_lshl_add_u64 v[94:95], s[0:1], 0, v[0:1]
	s_add_i32 s9, s9, 0x10000
	s_mov_b32 m0, s9
	s_nop 0
	global_load_lds_dwordx4 v[94:95], off
	s_lshl_b32 s8, s7, 1
	s_add_i32 s8, s8, 1
	v_xor_b32_e32 v0, s8, v29
	v_lshlrev_b32_e32 v0, 4, v0
	s_lshl_b32 s9, s8, 11
	s_add_i32 s9, s9, 0x0
	v_add_u32_e32 v0, s9, v0
	v_lshl_add_u64 v[94:95], s[0:1], 0, v[0:1]
	s_add_i32 s9, s9, 0x10000
	s_mov_b32 m0, s9
	s_nop 0
	global_load_lds_dwordx4 v[94:95], off
	s_lshl_b32 s8, s7, 1
	s_add_i32 s8, s8, 1
	v_xor_b32_e32 v0, s8, v29
	v_lshlrev_b32_e32 v0, 4, v0
	s_lshl_b32 s9, s8, 11
	s_add_i32 s9, s9, 0x400
	v_add_u32_e32 v0, s9, v0
	v_lshl_add_u64 v[94:95], s[0:1], 0, v[0:1]
	s_add_i32 s9, s9, 0x10000
	s_mov_b32 m0, s9
	s_nop 0
	global_load_lds_dwordx4 v[94:95], off
	s_add_u32 s8, s10, 0x0
	s_addc_u32 s9, s11, 0
	v_mov_b32_e32 v0, v90
	v_lshl_add_u64 v[94:95], s[8:9], 0, v[0:1]
	s_add_i32 s8, s12, 0x0
	s_mov_b32 m0, s8
	s_nop 0
	global_load_lds_dwordx4 v[94:95], off
	s_add_u32 s8, s10, 0x2000
	s_addc_u32 s9, s11, 0
	v_mov_b32_e32 v0, v91
	v_lshl_add_u64 v[94:95], s[8:9], 0, v[0:1]
	s_add_i32 s8, s12, 0x400
	s_mov_b32 m0, s8
	s_nop 0
	global_load_lds_dwordx4 v[94:95], off
	s_add_u32 s8, s10, 0x4000
	s_addc_u32 s9, s11, 0
	v_mov_b32_e32 v0, v92
	v_lshl_add_u64 v[94:95], s[8:9], 0, v[0:1]
	s_add_i32 s8, s12, 0x800
	s_mov_b32 m0, s8
	s_nop 0
	global_load_lds_dwordx4 v[94:95], off
	s_add_u32 s8, s10, 0x6000
	s_addc_u32 s9, s11, 0
	v_mov_b32_e32 v0, v93
	v_lshl_add_u64 v[94:95], s[8:9], 0, v[0:1]
	s_add_i32 s8, s12, 0xc00
	s_mov_b32 m0, s8
	s_nop 0
	global_load_lds_dwordx4 v[94:95], off
	s_add_u32 s8, s10, 0x100
	s_addc_u32 s9, s11, 0
	v_mov_b32_e32 v0, v90
	v_lshl_add_u64 v[94:95], s[8:9], 0, v[0:1]
	s_add_i32 s8, s12, 0x1000
	s_mov_b32 m0, s8
	s_nop 0
	global_load_lds_dwordx4 v[94:95], off
	s_add_u32 s8, s10, 0x2100
	s_addc_u32 s9, s11, 0
	v_mov_b32_e32 v0, v91
	v_lshl_add_u64 v[94:95], s[8:9], 0, v[0:1]
	s_add_i32 s8, s12, 0x1400
	s_mov_b32 m0, s8
	s_nop 0
	global_load_lds_dwordx4 v[94:95], off
	s_add_u32 s8, s10, 0x4100
	s_addc_u32 s9, s11, 0
	v_mov_b32_e32 v0, v92
	v_lshl_add_u64 v[94:95], s[8:9], 0, v[0:1]
	s_add_i32 s8, s12, 0x1800
	s_mov_b32 m0, s8
	s_nop 0
	global_load_lds_dwordx4 v[94:95], off
	s_add_u32 s8, s10, 0x6100
	s_addc_u32 s9, s11, 0
	v_mov_b32_e32 v0, v93
	v_lshl_add_u64 v[94:95], s[8:9], 0, v[0:1]
	s_add_i32 s8, s12, 0x1c00
	s_mov_b32 m0, s8
	s_nop 0
	global_load_lds_dwordx4 v[94:95], off
	s_waitcnt vmcnt(8)
	s_barrier
	s_waitcnt vmcnt(4)
	ds_read_b128 v[74:77], v34 offset:0
	ds_read_b128 v[42:45], v38 offset:0
	ds_read_b128 v[78:81], v35 offset:0
	ds_read_b128 v[46:49], v39 offset:0
	ds_read_b128 v[82:85], v36 offset:0
	ds_read_b128 v[50:53], v40 offset:0
	ds_read_b128 v[86:89], v37 offset:0
	ds_read_b128 v[54:57], v41 offset:0
	s_waitcnt lgkmcnt(0)
	s_add_u32 s8, s10, 0x200
	s_addc_u32 s9, s11, 0
	v_mov_b32_e32 v0, v90
	v_lshl_add_u64 v[94:95], s[8:9], 0, v[0:1]
	s_add_i32 s8, s12, 0x0
	s_mov_b32 m0, s8
	s_nop 0
	global_load_lds_dwordx4 v[94:95], off
	s_add_u32 s8, s10, 0x2200
	s_addc_u32 s9, s11, 0
	v_mov_b32_e32 v0, v91
	v_lshl_add_u64 v[94:95], s[8:9], 0, v[0:1]
	s_add_i32 s8, s12, 0x400
	s_mov_b32 m0, s8
	s_nop 0
	global_load_lds_dwordx4 v[94:95], off
	s_add_u32 s8, s10, 0x4200
	s_addc_u32 s9, s11, 0
	v_mov_b32_e32 v0, v92
	v_lshl_add_u64 v[94:95], s[8:9], 0, v[0:1]
	s_add_i32 s8, s12, 0x800
	s_mov_b32 m0, s8
	s_nop 0
	global_load_lds_dwordx4 v[94:95], off
	s_add_u32 s8, s10, 0x6200
	s_addc_u32 s9, s11, 0
	v_mov_b32_e32 v0, v93
	v_lshl_add_u64 v[94:95], s[8:9], 0, v[0:1]
	s_add_i32 s8, s12, 0xc00
	s_mov_b32 m0, s8
	s_nop 0
	global_load_lds_dwordx4 v[94:95], off
	v_mfma_f32_16x16x32_bf16 v[2:5], v[42:45], v[74:77], v[2:5]
	v_mfma_f32_16x16x32_bf16 v[2:5], v[46:49], v[78:81], v[2:5]
	v_mfma_f32_16x16x32_bf16 v[2:5], v[50:53], v[82:85], v[2:5]
	v_mfma_f32_16x16x32_bf16 v[2:5], v[54:57], v[86:89], v[2:5]
	s_waitcnt vmcnt(4)
	ds_read_b128 v[74:77], v34 offset:4096
	ds_read_b128 v[42:45], v38 offset:256
	ds_read_b128 v[78:81], v35 offset:4096
	ds_read_b128 v[46:49], v39 offset:256
	ds_read_b128 v[82:85], v36 offset:4096
	ds_read_b128 v[50:53], v40 offset:256
	ds_read_b128 v[86:89], v37 offset:4096
	ds_read_b128 v[54:57], v41 offset:256
	s_waitcnt lgkmcnt(0)
	s_add_u32 s8, s10, 0x300
	s_addc_u32 s9, s11, 0
	v_mov_b32_e32 v0, v90
	v_lshl_add_u64 v[94:95], s[8:9], 0, v[0:1]
	s_add_i32 s8, s12, 0x1000
	s_mov_b32 m0, s8
	s_nop 0
	global_load_lds_dwordx4 v[94:95], off
	s_add_u32 s8, s10, 0x2300
	s_addc_u32 s9, s11, 0
	v_mov_b32_e32 v0, v91
	v_lshl_add_u64 v[94:95], s[8:9], 0, v[0:1]
	s_add_i32 s8, s12, 0x1400
	s_mov_b32 m0, s8
	s_nop 0
	global_load_lds_dwordx4 v[94:95], off
	s_add_u32 s8, s10, 0x4300
	s_addc_u32 s9, s11, 0
	v_mov_b32_e32 v0, v92
	v_lshl_add_u64 v[94:95], s[8:9], 0, v[0:1]
	s_add_i32 s8, s12, 0x1800
	s_mov_b32 m0, s8
	s_nop 0
	global_load_lds_dwordx4 v[94:95], off
	s_add_u32 s8, s10, 0x6300
	s_addc_u32 s9, s11, 0
	v_mov_b32_e32 v0, v93
	v_lshl_add_u64 v[94:95], s[8:9], 0, v[0:1]
	s_add_i32 s8, s12, 0x1c00
	s_mov_b32 m0, s8
	s_nop 0
	global_load_lds_dwordx4 v[94:95], off
	v_mfma_f32_16x16x32_bf16 v[2:5], v[42:45], v[74:77], v[2:5]
	v_mfma_f32_16x16x32_bf16 v[2:5], v[46:49], v[78:81], v[2:5]
	v_mfma_f32_16x16x32_bf16 v[2:5], v[50:53], v[82:85], v[2:5]
	v_mfma_f32_16x16x32_bf16 v[2:5], v[54:57], v[86:89], v[2:5]
	s_waitcnt vmcnt(4)
	ds_read_b128 v[74:77], v34 offset:0
	ds_read_b128 v[42:45], v38 offset:512
	ds_read_b128 v[78:81], v35 offset:0
	ds_read_b128 v[46:49], v39 offset:512
	ds_read_b128 v[82:85], v36 offset:0
	ds_read_b128 v[50:53], v40 offset:512
	ds_read_b128 v[86:89], v37 offset:0
	ds_read_b128 v[54:57], v41 offset:512
	s_waitcnt lgkmcnt(0)
	s_add_u32 s8, s10, 0x400
	s_addc_u32 s9, s11, 0
	v_mov_b32_e32 v0, v90
	v_lshl_add_u64 v[94:95], s[8:9], 0, v[0:1]
	s_add_i32 s8, s12, 0x0
	s_mov_b32 m0, s8
	s_nop 0
	global_load_lds_dwordx4 v[94:95], off
	s_add_u32 s8, s10, 0x2400
	s_addc_u32 s9, s11, 0
	v_mov_b32_e32 v0, v91
	v_lshl_add_u64 v[94:95], s[8:9], 0, v[0:1]
	s_add_i32 s8, s12, 0x400
	s_mov_b32 m0, s8
	s_nop 0
	global_load_lds_dwordx4 v[94:95], off
	s_add_u32 s8, s10, 0x4400
	s_addc_u32 s9, s11, 0
	v_mov_b32_e32 v0, v92
	v_lshl_add_u64 v[94:95], s[8:9], 0, v[0:1]
	s_add_i32 s8, s12, 0x800
	s_mov_b32 m0, s8
	s_nop 0
	global_load_lds_dwordx4 v[94:95], off
	s_add_u32 s8, s10, 0x6400
	s_addc_u32 s9, s11, 0
	v_mov_b32_e32 v0, v93
	v_lshl_add_u64 v[94:95], s[8:9], 0, v[0:1]
	s_add_i32 s8, s12, 0xc00
	s_mov_b32 m0, s8
	s_nop 0
	global_load_lds_dwordx4 v[94:95], off
	v_mfma_f32_16x16x32_bf16 v[2:5], v[42:45], v[74:77], v[2:5]
	v_mfma_f32_16x16x32_bf16 v[2:5], v[46:49], v[78:81], v[2:5]
	v_mfma_f32_16x16x32_bf16 v[2:5], v[50:53], v[82:85], v[2:5]
	v_mfma_f32_16x16x32_bf16 v[2:5], v[54:57], v[86:89], v[2:5]
	s_waitcnt vmcnt(4)
	ds_read_b128 v[74:77], v34 offset:4096
	ds_read_b128 v[42:45], v38 offset:768
	ds_read_b128 v[78:81], v35 offset:4096
	ds_read_b128 v[46:49], v39 offset:768
	ds_read_b128 v[82:85], v36 offset:4096
	ds_read_b128 v[50:53], v40 offset:768
	ds_read_b128 v[86:89], v37 offset:4096
	ds_read_b128 v[54:57], v41 offset:768
	s_waitcnt lgkmcnt(0)
	s_add_u32 s8, s10, 0x500
	s_addc_u32 s9, s11, 0
	v_mov_b32_e32 v0, v90
	v_lshl_add_u64 v[94:95], s[8:9], 0, v[0:1]
	s_add_i32 s8, s12, 0x1000
	s_mov_b32 m0, s8
	s_nop 0
	global_load_lds_dwordx4 v[94:95], off
	s_add_u32 s8, s10, 0x2500
	s_addc_u32 s9, s11, 0
	v_mov_b32_e32 v0, v91
	v_lshl_add_u64 v[94:95], s[8:9], 0, v[0:1]
	s_add_i32 s8, s12, 0x1400
	s_mov_b32 m0, s8
	s_nop 0
	global_load_lds_dwordx4 v[94:95], off
	s_add_u32 s8, s10, 0x4500
	s_addc_u32 s9, s11, 0
	v_mov_b32_e32 v0, v92
	v_lshl_add_u64 v[94:95], s[8:9], 0, v[0:1]
	s_add_i32 s8, s12, 0x1800
	s_mov_b32 m0, s8
	s_nop 0
	global_load_lds_dwordx4 v[94:95], off
	s_add_u32 s8, s10, 0x6500
	s_addc_u32 s9, s11, 0
	v_mov_b32_e32 v0, v93
	v_lshl_add_u64 v[94:95], s[8:9], 0, v[0:1]
	s_add_i32 s8, s12, 0x1c00
	s_mov_b32 m0, s8
	s_nop 0
	global_load_lds_dwordx4 v[94:95], off
	v_mfma_f32_16x16x32_bf16 v[2:5], v[42:45], v[74:77], v[2:5]
	v_mfma_f32_16x16x32_bf16 v[2:5], v[46:49], v[78:81], v[2:5]
	v_mfma_f32_16x16x32_bf16 v[2:5], v[50:53], v[82:85], v[2:5]
	v_mfma_f32_16x16x32_bf16 v[2:5], v[54:57], v[86:89], v[2:5]
	s_waitcnt vmcnt(4)
	ds_read_b128 v[74:77], v34 offset:0
	ds_read_b128 v[42:45], v38 offset:1024
	ds_read_b128 v[78:81], v35 offset:0
	ds_read_b128 v[46:49], v39 offset:1024
	ds_read_b128 v[82:85], v36 offset:0
	ds_read_b128 v[50:53], v40 offset:1024
	ds_read_b128 v[86:89], v37 offset:0
	ds_read_b128 v[54:57], v41 offset:1024
	s_waitcnt lgkmcnt(0)
	s_add_u32 s8, s10, 0x600
	s_addc_u32 s9, s11, 0
	v_mov_b32_e32 v0, v90
	v_lshl_add_u64 v[94:95], s[8:9], 0, v[0:1]
	s_add_i32 s8, s12, 0x0
	s_mov_b32 m0, s8
	s_nop 0
	global_load_lds_dwordx4 v[94:95], off
	s_add_u32 s8, s10, 0x2600
	s_addc_u32 s9, s11, 0
	v_mov_b32_e32 v0, v91
	v_lshl_add_u64 v[94:95], s[8:9], 0, v[0:1]
	s_add_i32 s8, s12, 0x400
	s_mov_b32 m0, s8
	s_nop 0
	global_load_lds_dwordx4 v[94:95], off
	s_add_u32 s8, s10, 0x4600
	s_addc_u32 s9, s11, 0
	v_mov_b32_e32 v0, v92
	v_lshl_add_u64 v[94:95], s[8:9], 0, v[0:1]
	s_add_i32 s8, s12, 0x800
	s_mov_b32 m0, s8
	s_nop 0
	global_load_lds_dwordx4 v[94:95], off
	s_add_u32 s8, s10, 0x6600
	s_addc_u32 s9, s11, 0
	v_mov_b32_e32 v0, v93
	v_lshl_add_u64 v[94:95], s[8:9], 0, v[0:1]
	s_add_i32 s8, s12, 0xc00
	s_mov_b32 m0, s8
	s_nop 0
	global_load_lds_dwordx4 v[94:95], off
	v_mfma_f32_16x16x32_bf16 v[2:5], v[42:45], v[74:77], v[2:5]
	v_mfma_f32_16x16x32_bf16 v[2:5], v[46:49], v[78:81], v[2:5]
	v_mfma_f32_16x16x32_bf16 v[2:5], v[50:53], v[82:85], v[2:5]
	v_mfma_f32_16x16x32_bf16 v[2:5], v[54:57], v[86:89], v[2:5]
	s_waitcnt vmcnt(4)
	ds_read_b128 v[74:77], v34 offset:4096
	ds_read_b128 v[42:45], v38 offset:1280
	ds_read_b128 v[78:81], v35 offset:4096
	ds_read_b128 v[46:49], v39 offset:1280
	ds_read_b128 v[82:85], v36 offset:4096
	ds_read_b128 v[50:53], v40 offset:1280
	ds_read_b128 v[86:89], v37 offset:4096
	ds_read_b128 v[54:57], v41 offset:1280
	s_waitcnt lgkmcnt(0)
	s_add_u32 s8, s10, 0x700
	s_addc_u32 s9, s11, 0
	v_mov_b32_e32 v0, v90
	v_lshl_add_u64 v[94:95], s[8:9], 0, v[0:1]
	s_add_i32 s8, s12, 0x1000
	s_mov_b32 m0, s8
	s_nop 0
	global_load_lds_dwordx4 v[94:95], off
	s_add_u32 s8, s10, 0x2700
	s_addc_u32 s9, s11, 0
	v_mov_b32_e32 v0, v91
	v_lshl_add_u64 v[94:95], s[8:9], 0, v[0:1]
	s_add_i32 s8, s12, 0x1400
	s_mov_b32 m0, s8
	s_nop 0
	global_load_lds_dwordx4 v[94:95], off
	s_add_u32 s8, s10, 0x4700
	s_addc_u32 s9, s11, 0
	v_mov_b32_e32 v0, v92
	v_lshl_add_u64 v[94:95], s[8:9], 0, v[0:1]
	s_add_i32 s8, s12, 0x1800
	s_mov_b32 m0, s8
	s_nop 0
	global_load_lds_dwordx4 v[94:95], off
	s_add_u32 s8, s10, 0x6700
	s_addc_u32 s9, s11, 0
	v_mov_b32_e32 v0, v93
	v_lshl_add_u64 v[94:95], s[8:9], 0, v[0:1]
	s_add_i32 s8, s12, 0x1c00
	s_mov_b32 m0, s8
	s_nop 0
	global_load_lds_dwordx4 v[94:95], off
	v_mfma_f32_16x16x32_bf16 v[2:5], v[42:45], v[74:77], v[2:5]
	v_mfma_f32_16x16x32_bf16 v[2:5], v[46:49], v[78:81], v[2:5]
	v_mfma_f32_16x16x32_bf16 v[2:5], v[50:53], v[82:85], v[2:5]
	v_mfma_f32_16x16x32_bf16 v[2:5], v[54:57], v[86:89], v[2:5]
	s_waitcnt vmcnt(4)
	ds_read_b128 v[74:77], v34 offset:0
	ds_read_b128 v[42:45], v38 offset:1536
	ds_read_b128 v[78:81], v35 offset:0
	ds_read_b128 v[46:49], v39 offset:1536
	ds_read_b128 v[82:85], v36 offset:0
	ds_read_b128 v[50:53], v40 offset:1536
	ds_read_b128 v[86:89], v37 offset:0
	ds_read_b128 v[54:57], v41 offset:1536
	s_waitcnt lgkmcnt(0)
	v_mfma_f32_16x16x32_bf16 v[2:5], v[42:45], v[74:77], v[2:5]
	v_mfma_f32_16x16x32_bf16 v[2:5], v[46:49], v[78:81], v[2:5]
	v_mfma_f32_16x16x32_bf16 v[2:5], v[50:53], v[82:85], v[2:5]
	v_mfma_f32_16x16x32_bf16 v[2:5], v[54:57], v[86:89], v[2:5]
	s_waitcnt vmcnt(0)
	ds_read_b128 v[74:77], v34 offset:4096
	ds_read_b128 v[42:45], v38 offset:1792
	ds_read_b128 v[78:81], v35 offset:4096
	ds_read_b128 v[46:49], v39 offset:1792
	ds_read_b128 v[82:85], v36 offset:4096
	ds_read_b128 v[50:53], v40 offset:1792
	ds_read_b128 v[86:89], v37 offset:4096
	ds_read_b128 v[54:57], v41 offset:1792
	s_waitcnt lgkmcnt(0)
	v_mfma_f32_16x16x32_bf16 v[2:5], v[42:45], v[74:77], v[2:5]
	v_mfma_f32_16x16x32_bf16 v[2:5], v[46:49], v[78:81], v[2:5]
	v_mfma_f32_16x16x32_bf16 v[2:5], v[50:53], v[82:85], v[2:5]
	v_mfma_f32_16x16x32_bf16 v[2:5], v[54:57], v[86:89], v[2:5]
	s_mov_b32 m0, s13
	s_barrier
	s_and_saveexec_b64 s[0:1], s[36:37]
	s_cbranch_execz .LBB0_484
	v_lshl_add_u32 v0, s4, 7, v25
	v_or_b32_e32 v18, v0, v24
	v_ashrrev_i32_e32 v19, 31, v18
	v_lshlrev_b64 v[18:19], 6, v[18:19]
	v_lshl_add_u64 v[22:23], s[30:31], 0, v[18:19]
	global_load_dwordx4 v[18:21], v[22:23], off offset:48
	global_load_dwordx4 v[30:33], v[22:23], off offset:32
	global_load_dwordx4 v[34:37], v[22:23], off offset:16
	global_load_dwordx4 v[38:41], v[22:23], off
	s_movk_i32 s6, 0xfff
	s_mov_b32 s8, 0x42ce8ed0
	s_mov_b32 s9, 0xc2b17218
	s_mov_b32 s11, 0x3f2aaaab
	s_mov_b32 s12, 0x3f317218
	s_mov_b32 s10, 0x7f800000
	s_mov_b32 s13, 0x33800000
	s_waitcnt vmcnt(2)
	v_add_f32_e32 v30, v30, v31
	v_add_f32_e32 v32, v32, v33
	s_waitcnt vmcnt(0)
	v_mov_b32_e32 v22, v39
	v_mov_b32_e32 v23, v40
	v_mov_b32_e32 v39, v41
	v_pk_add_f32 v[22:23], v[22:23], v[38:39]
	v_mov_b32_e32 v38, v35
	v_mov_b32_e32 v39, v36
	v_mov_b32_e32 v35, v37
	v_pk_add_f32 v[34:35], v[38:39], v[34:35]
	v_pk_add_f32 v[22:23], v[22:23], v[22:23] op_sel:[0,1] op_sel_hi:[1,0]
	v_pk_add_f32 v[34:35], v[34:35], v[34:35] op_sel:[0,1] op_sel_hi:[1,0]
	v_mov_b32_e32 v23, v18
	v_mov_b32_e32 v35, v19
	v_mov_b32_e32 v31, v20
	v_mov_b32_e32 v33, v21
	v_pk_add_f32 v[18:19], v[22:23], v[34:35]
	v_pk_add_f32 v[20:21], v[30:31], v[32:33]
	s_nop 0
	v_pk_add_f32 v[18:19], v[18:19], v[20:21]
	s_nop 0
	v_add_f32_e32 v7, v18, v19
	v_fmamk_f32 v7, v7, 0x3a800000, v214
	v_bitop3_b32 v18, v0, s6, v24 bitop3:0xc8
	v_ashrrev_i32_e32 v0, 9, v0
	v_readlane_b32 s6, v252, 20
	v_rsq_f32_e32 v15, v7
	v_and_b32_e32 v7, -8, v0
	v_lshlrev_b32_e32 v0, 2, v18
	v_readlane_b32 s7, v252, 21
	s_nop 1
	v_lshl_add_u64 v[18:19], s[6:7], 0, v[0:1]
	global_load_dword v0, v[8:9], off
	global_load_dword v100, v[10:11], off offset:4
	global_load_dword v101, v[10:11], off offset:8
	global_load_dword v102, v[10:11], off offset:12
	s_mov_b32 s6, 0xbfb8aa3b
	s_mov_b32 s7, 0xb2a5705f
	s_waitcnt vmcnt(0)
	v_fmac_f32_e32 v0, v2, v15
	v_mul_f32_e64 v20, |v0|, s6
	v_fma_f32 v21, |v0|, s6, -v20
	v_rndne_f32_e32 v22, v20
	v_fma_f32 v21, |v0|, s7, v21
	v_sub_f32_e32 v20, v20, v22
	v_add_f32_e32 v20, v20, v21
	v_exp_f32_e32 v20, v20
	v_cvt_i32_f32_e32 v21, v22
	v_cmp_ngt_f32_e64 vcc, |v0|, s8
	v_min_f32_e32 v2, 0, v0
	v_ldexp_f32 v20, v20, v21
	v_cndmask_b32_e32 v20, 0, v20, vcc
	v_cmp_nlt_f32_e64 vcc, |v0|, s9
	s_nop 1
	v_cndmask_b32_e32 v0, v223, v20, vcc
	v_add_f32_e32 v22, 1.0, v0
	v_add_f32_e32 v20, -1.0, v22
	v_sub_f32_e32 v21, v20, v22
	v_add_f32_e32 v21, 1.0, v21
	v_sub_f32_e32 v20, v0, v20
	v_add_f32_e32 v23, v20, v21
	v_frexp_mant_f32_e32 v20, v22
	v_cmp_gt_f32_e32 vcc, s11, v20
	v_cvt_f64_f32_e32 v[20:21], v22
	v_frexp_exp_i32_f64_e32 v20, v[20:21]
	v_subbrev_co_u32_e32 v20, vcc, 0, v20, vcc
	v_sub_u32_e32 v21, 0, v20
	v_ldexp_f32 v22, v22, v21
	v_ldexp_f32 v21, v23, v21
	v_add_f32_e32 v23, -1.0, v22
	v_add_f32_e32 v29, 1.0, v23
	v_sub_f32_e32 v29, v22, v29
	v_add_f32_e32 v29, v21, v29
	v_add_f32_e32 v30, v23, v29
	v_sub_f32_e32 v23, v23, v30
	v_add_f32_e32 v23, v29, v23
	v_add_f32_e32 v29, 1.0, v22
	v_add_f32_e32 v31, -1.0, v29
	v_sub_f32_e32 v22, v22, v31
	v_add_f32_e32 v21, v21, v22
	v_add_f32_e32 v22, v29, v21
	v_sub_f32_e32 v29, v29, v22
	v_add_f32_e32 v21, v21, v29
	v_rcp_f32_e32 v29, v22
	v_cvt_f32_i32_e32 v20, v20
	v_cmp_neq_f32_e32 vcc, s10, v0
	v_mul_f32_e32 v31, v30, v29
	v_mul_f32_e32 v32, v22, v31
	v_fma_f32 v33, v31, v22, -v32
	v_fmac_f32_e32 v33, v31, v21
	v_add_f32_e32 v34, v32, v33
	v_sub_f32_e32 v35, v30, v34
	v_sub_f32_e32 v30, v30, v35
	v_sub_f32_e32 v32, v34, v32
	v_sub_f32_e32 v30, v30, v34
	v_add_f32_e32 v23, v23, v30
	v_sub_f32_e32 v30, v32, v33
	v_add_f32_e32 v23, v30, v23
	v_add_f32_e32 v30, v35, v23
	v_mul_f32_e32 v32, v29, v30
	v_mul_f32_e32 v33, v22, v32
	v_fma_f32 v22, v32, v22, -v33
	v_fmac_f32_e32 v22, v32, v21
	v_sub_f32_e32 v21, v35, v30
	v_add_f32_e32 v21, v23, v21
	v_add_f32_e32 v23, v33, v22
	v_sub_f32_e32 v34, v30, v23
	v_sub_f32_e32 v30, v30, v34
	v_sub_f32_e32 v33, v23, v33
	v_sub_f32_e32 v23, v30, v23
	v_add_f32_e32 v21, v21, v23
	v_sub_f32_e32 v22, v33, v22
	v_add_f32_e32 v21, v22, v21
	v_add_f32_e32 v22, v31, v32
	v_add_f32_e32 v21, v34, v21
	v_sub_f32_e32 v23, v22, v31
	v_mul_f32_e32 v21, v29, v21
	v_sub_f32_e32 v23, v32, v23
	v_add_f32_e32 v21, v23, v21
	v_mul_f32_e32 v31, 0x3f317218, v20
	v_add_f32_e32 v23, v22, v21
	v_fma_f32 v32, v20, s12, -v31
	v_mul_f32_e32 v29, v23, v23
	v_fmac_f32_e32 v32, 0xb102e308, v20
	v_sub_f32_e32 v20, v23, v22
	v_fmamk_f32 v30, v29, 0x3e9b6dac, v215
	v_sub_f32_e32 v20, v21, v20
	v_add_f32_e32 v21, v31, v32
	v_fmaak_f32 v30, v29, v30, 0x3f2aaada
	v_sub_f32_e32 v22, v21, v31
	v_ldexp_f32 v31, v23, 1
	v_mul_f32_e32 v23, v23, v29
	v_mul_f32_e32 v23, v23, v30
	v_add_f32_e32 v29, v31, v23
	v_sub_f32_e32 v30, v29, v31
	v_ldexp_f32 v20, v20, 1
	v_sub_f32_e32 v23, v23, v30
	v_add_f32_e32 v20, v20, v23
	v_add_f32_e32 v23, v29, v20
	v_sub_f32_e32 v29, v23, v29
	v_sub_f32_e32 v20, v20, v29
	v_add_f32_e32 v29, v21, v23
	v_sub_f32_e32 v30, v29, v21
	v_sub_f32_e32 v31, v29, v30
	v_sub_f32_e32 v22, v32, v22
	v_sub_f32_e32 v21, v21, v31
	v_sub_f32_e32 v23, v23, v30
	v_add_f32_e32 v21, v23, v21
	v_add_f32_e32 v23, v22, v20
	v_sub_f32_e32 v30, v23, v22
	v_sub_f32_e32 v31, v23, v30
	v_sub_f32_e32 v22, v22, v31
	v_sub_f32_e32 v20, v20, v30
	v_add_f32_e32 v21, v23, v21
	v_add_f32_e32 v20, v20, v22
	v_add_f32_e32 v22, v29, v21
	v_sub_f32_e32 v23, v22, v29
	v_sub_f32_e32 v21, v21, v23
	v_add_f32_e32 v20, v20, v21
	v_add_f32_e32 v20, v22, v20
	v_cndmask_b32_e32 v20, v223, v20, vcc
	v_cmp_lt_f32_e64 vcc, |v0|, s13
	s_nop 1
	v_cndmask_b32_e32 v0, v20, v0, vcc
	v_or_b32_e32 v20, v7, v6
	v_ashrrev_i32_e32 v21, 31, v20
	v_lshlrev_b64 v[20:21], 14, v[20:21]
	v_sub_f32_e32 v0, v2, v0
	v_lshl_add_u64 v[20:21], v[18:19], 0, v[20:21]
	global_store_dword v[20:21], v0, off
	v_mov_b32_e32 v0, v100
	v_fmac_f32_e32 v0, v3, v15
	v_mul_f32_e64 v2, |v0|, s6
	v_fma_f32 v3, |v0|, s6, -v2
	v_rndne_f32_e32 v21, v2
	v_fma_f32 v3, |v0|, s7, v3
	v_sub_f32_e32 v2, v2, v21
	v_add_f32_e32 v2, v2, v3
	v_exp_f32_e32 v2, v2
	v_cvt_i32_f32_e32 v3, v21
	v_cmp_ngt_f32_e64 vcc, |v0|, s8
	v_min_f32_e32 v20, 0, v0
	v_ldexp_f32 v2, v2, v3
	v_cndmask_b32_e32 v2, 0, v2, vcc
	v_cmp_nlt_f32_e64 vcc, |v0|, s9
	s_nop 1
	v_cndmask_b32_e32 v0, v223, v2, vcc
	v_add_f32_e32 v21, 1.0, v0
	v_add_f32_e32 v2, -1.0, v21
	v_sub_f32_e32 v3, v2, v21
	v_add_f32_e32 v3, 1.0, v3
	v_sub_f32_e32 v2, v0, v2
	v_add_f32_e32 v22, v2, v3
	v_frexp_mant_f32_e32 v2, v21
	v_cmp_gt_f32_e32 vcc, s11, v2
	v_cvt_f64_f32_e32 v[2:3], v21
	v_frexp_exp_i32_f64_e32 v2, v[2:3]
	v_subbrev_co_u32_e32 v2, vcc, 0, v2, vcc
	v_sub_u32_e32 v3, 0, v2
	v_ldexp_f32 v21, v21, v3
	v_ldexp_f32 v3, v22, v3
	v_add_f32_e32 v22, -1.0, v21
	v_add_f32_e32 v23, 1.0, v22
	v_sub_f32_e32 v23, v21, v23
	v_add_f32_e32 v23, v3, v23
	v_add_f32_e32 v29, v22, v23
	v_sub_f32_e32 v22, v22, v29
	v_add_f32_e32 v22, v23, v22
	v_add_f32_e32 v23, 1.0, v21
	v_add_f32_e32 v30, -1.0, v23
	v_sub_f32_e32 v21, v21, v30
	v_add_f32_e32 v3, v3, v21
	v_add_f32_e32 v21, v23, v3
	v_sub_f32_e32 v23, v23, v21
	v_add_f32_e32 v3, v3, v23
	v_rcp_f32_e32 v23, v21
	v_cvt_f32_i32_e32 v2, v2
	v_cmp_neq_f32_e32 vcc, s10, v0
	v_mul_f32_e32 v30, v29, v23
	v_mul_f32_e32 v31, v21, v30
	v_fma_f32 v32, v30, v21, -v31
	v_fmac_f32_e32 v32, v30, v3
	v_add_f32_e32 v33, v31, v32
	v_sub_f32_e32 v34, v29, v33
	v_sub_f32_e32 v29, v29, v34
	v_sub_f32_e32 v31, v33, v31
	v_sub_f32_e32 v29, v29, v33
	v_add_f32_e32 v22, v22, v29
	v_sub_f32_e32 v29, v31, v32
	v_add_f32_e32 v22, v29, v22
	v_add_f32_e32 v29, v34, v22
	v_mul_f32_e32 v31, v23, v29
	v_mul_f32_e32 v32, v21, v31
	v_fma_f32 v21, v31, v21, -v32
	v_fmac_f32_e32 v21, v31, v3
	v_sub_f32_e32 v3, v34, v29
	v_add_f32_e32 v3, v22, v3
	v_add_f32_e32 v22, v32, v21
	v_sub_f32_e32 v33, v29, v22
	v_sub_f32_e32 v29, v29, v33
	v_sub_f32_e32 v32, v22, v32
	v_sub_f32_e32 v22, v29, v22
	v_add_f32_e32 v3, v3, v22
	v_sub_f32_e32 v21, v32, v21
	v_add_f32_e32 v3, v21, v3
	v_add_f32_e32 v21, v30, v31
	v_add_f32_e32 v3, v33, v3
	v_sub_f32_e32 v22, v21, v30
	v_mul_f32_e32 v3, v23, v3
	v_sub_f32_e32 v22, v31, v22
	v_add_f32_e32 v3, v22, v3
	v_mul_f32_e32 v30, 0x3f317218, v2
	v_add_f32_e32 v22, v21, v3
	v_fma_f32 v31, v2, s12, -v30
	v_mul_f32_e32 v23, v22, v22
	v_fmac_f32_e32 v31, 0xb102e308, v2
	v_sub_f32_e32 v2, v22, v21
	v_fmamk_f32 v29, v23, 0x3e9b6dac, v215
	v_sub_f32_e32 v2, v3, v2
	v_add_f32_e32 v3, v30, v31
	v_fmaak_f32 v29, v23, v29, 0x3f2aaada
	v_sub_f32_e32 v21, v3, v30
	v_ldexp_f32 v30, v22, 1
	v_mul_f32_e32 v22, v22, v23
	v_mul_f32_e32 v22, v22, v29
	v_add_f32_e32 v23, v30, v22
	v_sub_f32_e32 v29, v23, v30
	v_ldexp_f32 v2, v2, 1
	v_sub_f32_e32 v22, v22, v29
	v_add_f32_e32 v2, v2, v22
	v_add_f32_e32 v22, v23, v2
	v_sub_f32_e32 v23, v22, v23
	v_sub_f32_e32 v2, v2, v23
	v_add_f32_e32 v23, v3, v22
	v_sub_f32_e32 v29, v23, v3
	v_sub_f32_e32 v30, v23, v29
	v_sub_f32_e32 v21, v31, v21
	v_sub_f32_e32 v3, v3, v30
	v_sub_f32_e32 v22, v22, v29
	v_add_f32_e32 v3, v22, v3
	v_add_f32_e32 v22, v21, v2
	v_sub_f32_e32 v29, v22, v21
	v_sub_f32_e32 v30, v22, v29
	v_sub_f32_e32 v21, v21, v30
	v_sub_f32_e32 v2, v2, v29
	v_add_f32_e32 v3, v22, v3
	v_add_f32_e32 v2, v2, v21
	v_add_f32_e32 v21, v23, v3
	v_sub_f32_e32 v22, v21, v23
	v_sub_f32_e32 v3, v3, v22
	v_add_f32_e32 v2, v2, v3
	v_add_f32_e32 v2, v21, v2
	v_cndmask_b32_e32 v2, v223, v2, vcc
	v_cmp_lt_f32_e64 vcc, |v0|, s13
	s_nop 1
	v_cndmask_b32_e32 v0, v2, v0, vcc
	v_or_b32_e32 v2, v7, v26
	v_ashrrev_i32_e32 v3, 31, v2
	v_lshlrev_b64 v[2:3], 14, v[2:3]
	v_sub_f32_e32 v0, v20, v0
	v_lshl_add_u64 v[2:3], v[18:19], 0, v[2:3]
	global_store_dword v[2:3], v0, off
	v_mov_b32_e32 v0, v101
	v_fmac_f32_e32 v0, v4, v15
	v_mul_f32_e64 v2, |v0|, s6
	v_fma_f32 v3, |v0|, s6, -v2
	v_rndne_f32_e32 v20, v2
	v_fma_f32 v3, |v0|, s7, v3
	v_sub_f32_e32 v2, v2, v20
	v_add_f32_e32 v2, v2, v3
	v_exp_f32_e32 v2, v2
	v_cvt_i32_f32_e32 v3, v20
	v_cmp_ngt_f32_e64 vcc, |v0|, s8
	v_min_f32_e32 v4, 0, v0
	v_ldexp_f32 v2, v2, v3
	v_cndmask_b32_e32 v2, 0, v2, vcc
	v_cmp_nlt_f32_e64 vcc, |v0|, s9
	s_nop 1
	v_cndmask_b32_e32 v0, v223, v2, vcc
	v_add_f32_e32 v20, 1.0, v0
	v_add_f32_e32 v2, -1.0, v20
	v_sub_f32_e32 v3, v2, v20
	v_add_f32_e32 v3, 1.0, v3
	v_sub_f32_e32 v2, v0, v2
	v_add_f32_e32 v21, v2, v3
	v_frexp_mant_f32_e32 v2, v20
	v_cmp_gt_f32_e32 vcc, s11, v2
	v_cvt_f64_f32_e32 v[2:3], v20
	v_frexp_exp_i32_f64_e32 v2, v[2:3]
	v_subbrev_co_u32_e32 v2, vcc, 0, v2, vcc
	v_sub_u32_e32 v3, 0, v2
	v_ldexp_f32 v20, v20, v3
	v_ldexp_f32 v3, v21, v3
	v_add_f32_e32 v21, -1.0, v20
	v_add_f32_e32 v22, 1.0, v21
	v_sub_f32_e32 v22, v20, v22
	v_add_f32_e32 v22, v3, v22
	v_add_f32_e32 v23, v21, v22
	v_sub_f32_e32 v21, v21, v23
	v_add_f32_e32 v21, v22, v21
	v_add_f32_e32 v22, 1.0, v20
	v_add_f32_e32 v29, -1.0, v22
	v_sub_f32_e32 v20, v20, v29
	v_add_f32_e32 v3, v3, v20
	v_add_f32_e32 v20, v22, v3
	v_sub_f32_e32 v22, v22, v20
	v_add_f32_e32 v3, v3, v22
	v_rcp_f32_e32 v22, v20
	v_cvt_f32_i32_e32 v2, v2
	v_cmp_neq_f32_e32 vcc, s10, v0
	v_mul_f32_e32 v29, v23, v22
	v_mul_f32_e32 v30, v20, v29
	v_fma_f32 v31, v29, v20, -v30
	v_fmac_f32_e32 v31, v29, v3
	v_add_f32_e32 v32, v30, v31
	v_sub_f32_e32 v33, v23, v32
	v_sub_f32_e32 v23, v23, v33
	v_sub_f32_e32 v30, v32, v30
	v_sub_f32_e32 v23, v23, v32
	v_add_f32_e32 v21, v21, v23
	v_sub_f32_e32 v23, v30, v31
	v_add_f32_e32 v21, v23, v21
	v_add_f32_e32 v23, v33, v21
	v_mul_f32_e32 v30, v22, v23
	v_mul_f32_e32 v31, v20, v30
	v_fma_f32 v20, v30, v20, -v31
	v_fmac_f32_e32 v20, v30, v3
	v_sub_f32_e32 v3, v33, v23
	v_add_f32_e32 v3, v21, v3
	v_add_f32_e32 v21, v31, v20
	v_sub_f32_e32 v32, v23, v21
	v_sub_f32_e32 v23, v23, v32
	v_sub_f32_e32 v31, v21, v31
	v_sub_f32_e32 v21, v23, v21
	v_add_f32_e32 v3, v3, v21
	v_sub_f32_e32 v20, v31, v20
	v_add_f32_e32 v3, v20, v3
	v_add_f32_e32 v20, v29, v30
	v_add_f32_e32 v3, v32, v3
	v_sub_f32_e32 v21, v20, v29
	v_mul_f32_e32 v3, v22, v3
	v_sub_f32_e32 v21, v30, v21
	v_add_f32_e32 v3, v21, v3
	v_mul_f32_e32 v29, 0x3f317218, v2
	v_add_f32_e32 v21, v20, v3
	v_fma_f32 v30, v2, s12, -v29
	v_mul_f32_e32 v22, v21, v21
	v_fmac_f32_e32 v30, 0xb102e308, v2
	v_sub_f32_e32 v2, v21, v20
	v_fmamk_f32 v23, v22, 0x3e9b6dac, v215
	v_sub_f32_e32 v2, v3, v2
	v_add_f32_e32 v3, v29, v30
	v_fmaak_f32 v23, v22, v23, 0x3f2aaada
	v_sub_f32_e32 v20, v3, v29
	v_ldexp_f32 v29, v21, 1
	v_mul_f32_e32 v21, v21, v22
	v_mul_f32_e32 v21, v21, v23
	v_add_f32_e32 v22, v29, v21
	v_sub_f32_e32 v23, v22, v29
	v_ldexp_f32 v2, v2, 1
	v_sub_f32_e32 v21, v21, v23
	v_add_f32_e32 v2, v2, v21
	v_add_f32_e32 v21, v22, v2
	v_sub_f32_e32 v22, v21, v22
	v_sub_f32_e32 v2, v2, v22
	v_add_f32_e32 v22, v3, v21
	v_sub_f32_e32 v23, v22, v3
	v_sub_f32_e32 v29, v22, v23
	v_sub_f32_e32 v20, v30, v20
	v_sub_f32_e32 v3, v3, v29
	v_sub_f32_e32 v21, v21, v23
	v_add_f32_e32 v3, v21, v3
	v_add_f32_e32 v21, v20, v2
	v_sub_f32_e32 v23, v21, v20
	v_sub_f32_e32 v29, v21, v23
	v_sub_f32_e32 v20, v20, v29
	v_sub_f32_e32 v2, v2, v23
	v_add_f32_e32 v3, v21, v3
	v_add_f32_e32 v2, v2, v20
	v_add_f32_e32 v20, v22, v3
	v_sub_f32_e32 v21, v20, v22
	v_sub_f32_e32 v3, v3, v21
	v_add_f32_e32 v2, v2, v3
	v_add_f32_e32 v2, v20, v2
	v_cndmask_b32_e32 v2, v223, v2, vcc
	v_cmp_lt_f32_e64 vcc, |v0|, s13
	s_nop 1
	v_cndmask_b32_e32 v0, v2, v0, vcc
	v_or_b32_e32 v2, v7, v27
	v_ashrrev_i32_e32 v3, 31, v2
	v_lshlrev_b64 v[2:3], 14, v[2:3]
	v_sub_f32_e32 v0, v4, v0
	v_lshl_add_u64 v[2:3], v[18:19], 0, v[2:3]
	global_store_dword v[2:3], v0, off
	v_mov_b32_e32 v0, v102
	v_fmac_f32_e32 v0, v5, v15
	v_mul_f32_e64 v2, |v0|, s6
	v_fma_f32 v3, |v0|, s6, -v2
	v_rndne_f32_e32 v5, v2
	v_fma_f32 v3, |v0|, s7, v3
	v_sub_f32_e32 v2, v2, v5
	v_add_f32_e32 v2, v2, v3
	v_exp_f32_e32 v2, v2
	v_cvt_i32_f32_e32 v3, v5
	v_cmp_ngt_f32_e64 vcc, |v0|, s8
	v_min_f32_e32 v4, 0, v0
	v_ldexp_f32 v2, v2, v3
	v_cndmask_b32_e32 v2, 0, v2, vcc
	v_cmp_nlt_f32_e64 vcc, |v0|, s9
	s_nop 1
	v_cndmask_b32_e32 v0, v223, v2, vcc
	v_add_f32_e32 v5, 1.0, v0
	v_add_f32_e32 v2, -1.0, v5
	v_sub_f32_e32 v3, v2, v5
	v_add_f32_e32 v3, 1.0, v3
	v_sub_f32_e32 v2, v0, v2
	v_add_f32_e32 v15, v2, v3
	v_frexp_mant_f32_e32 v2, v5
	v_cmp_gt_f32_e32 vcc, s11, v2
	v_cvt_f64_f32_e32 v[2:3], v5
	v_frexp_exp_i32_f64_e32 v2, v[2:3]
	v_subbrev_co_u32_e32 v2, vcc, 0, v2, vcc
	v_sub_u32_e32 v3, 0, v2
	v_ldexp_f32 v5, v5, v3
	v_ldexp_f32 v3, v15, v3
	v_add_f32_e32 v15, -1.0, v5
	v_add_f32_e32 v20, 1.0, v15
	v_sub_f32_e32 v20, v5, v20
	v_add_f32_e32 v20, v3, v20
	v_add_f32_e32 v21, v15, v20
	v_sub_f32_e32 v15, v15, v21
	v_add_f32_e32 v15, v20, v15
	v_add_f32_e32 v20, 1.0, v5
	v_add_f32_e32 v22, -1.0, v20
	v_sub_f32_e32 v5, v5, v22
	v_add_f32_e32 v3, v3, v5
	v_add_f32_e32 v5, v20, v3
	v_sub_f32_e32 v20, v20, v5
	v_add_f32_e32 v3, v3, v20
	v_rcp_f32_e32 v20, v5
	v_cvt_f32_i32_e32 v2, v2
	v_cmp_neq_f32_e32 vcc, s10, v0
	v_mul_f32_e32 v22, v21, v20
	v_mul_f32_e32 v23, v5, v22
	v_fma_f32 v29, v22, v5, -v23
	v_fmac_f32_e32 v29, v22, v3
	v_add_f32_e32 v30, v23, v29
	v_sub_f32_e32 v31, v21, v30
	v_sub_f32_e32 v21, v21, v31
	v_sub_f32_e32 v23, v30, v23
	v_sub_f32_e32 v21, v21, v30
	v_add_f32_e32 v15, v15, v21
	v_sub_f32_e32 v21, v23, v29
	v_add_f32_e32 v15, v21, v15
	v_add_f32_e32 v21, v31, v15
	v_mul_f32_e32 v23, v20, v21
	v_mul_f32_e32 v29, v5, v23
	v_fma_f32 v5, v23, v5, -v29
	v_fmac_f32_e32 v5, v23, v3
	v_sub_f32_e32 v3, v31, v21
	v_add_f32_e32 v3, v15, v3
	v_add_f32_e32 v15, v29, v5
	v_sub_f32_e32 v30, v21, v15
	v_sub_f32_e32 v21, v21, v30
	v_sub_f32_e32 v29, v15, v29
	v_sub_f32_e32 v15, v21, v15
	v_add_f32_e32 v3, v3, v15
	v_sub_f32_e32 v5, v29, v5
	v_add_f32_e32 v3, v5, v3
	v_add_f32_e32 v5, v22, v23
	v_add_f32_e32 v3, v30, v3
	v_sub_f32_e32 v15, v5, v22
	v_mul_f32_e32 v3, v20, v3
	v_sub_f32_e32 v15, v23, v15
	v_add_f32_e32 v3, v15, v3
	v_mul_f32_e32 v22, 0x3f317218, v2
	v_add_f32_e32 v15, v5, v3
	v_fma_f32 v23, v2, s12, -v22
	v_mul_f32_e32 v20, v15, v15
	v_fmac_f32_e32 v23, 0xb102e308, v2
	v_sub_f32_e32 v2, v15, v5
	v_fmamk_f32 v21, v20, 0x3e9b6dac, v215
	v_sub_f32_e32 v2, v3, v2
	v_add_f32_e32 v3, v22, v23
	v_fmaak_f32 v21, v20, v21, 0x3f2aaada
	v_sub_f32_e32 v5, v3, v22
	v_ldexp_f32 v22, v15, 1
	v_mul_f32_e32 v15, v15, v20
	v_mul_f32_e32 v15, v15, v21
	v_add_f32_e32 v20, v22, v15
	v_sub_f32_e32 v21, v20, v22
	v_ldexp_f32 v2, v2, 1
	v_sub_f32_e32 v15, v15, v21
	v_add_f32_e32 v2, v2, v15
	v_add_f32_e32 v15, v20, v2
	v_sub_f32_e32 v20, v15, v20
	v_sub_f32_e32 v2, v2, v20
	v_add_f32_e32 v20, v3, v15
	v_sub_f32_e32 v21, v20, v3
	v_sub_f32_e32 v22, v20, v21
	v_sub_f32_e32 v5, v23, v5
	v_sub_f32_e32 v3, v3, v22
	v_sub_f32_e32 v15, v15, v21
	v_add_f32_e32 v3, v15, v3
	v_add_f32_e32 v15, v5, v2
	v_sub_f32_e32 v21, v15, v5
	v_sub_f32_e32 v22, v15, v21
	v_sub_f32_e32 v5, v5, v22
	v_sub_f32_e32 v2, v2, v21
	v_add_f32_e32 v3, v15, v3
	v_add_f32_e32 v2, v2, v5
	v_add_f32_e32 v5, v20, v3
	v_sub_f32_e32 v15, v5, v20
	v_sub_f32_e32 v3, v3, v15
	v_add_f32_e32 v2, v2, v3
	v_add_f32_e32 v2, v5, v2
	v_cndmask_b32_e32 v2, v223, v2, vcc
	v_cmp_lt_f32_e64 vcc, |v0|, s13
	s_nop 1
	v_cndmask_b32_e32 v0, v2, v0, vcc
	v_or_b32_e32 v2, v7, v28
	v_ashrrev_i32_e32 v3, 31, v2
	v_lshlrev_b64 v[2:3], 14, v[2:3]
	v_sub_f32_e32 v0, v4, v0
	v_lshl_add_u64 v[2:3], v[18:19], 0, v[2:3]
	global_store_dword v[2:3], v0, off
	s_branch .LBB0_484
